# v36 + P4: workgroups of odd heads run their weight-conversion share before the retention/attention units, even heads after
# speedup vs baseline: 1.0137x; 1.0052x over previous
; #define LAS __attribute__((address_space(3)))
; DI float gamma_of(int h) { return 1.0f - exp2f(-5.0f - (float)h); }
; DI void ret_step2(LAS unsigned char* lds, const bf16_t* Z, const bf16_t* SP, bf16_t* MIX, const float* rng, int n, int h, int tid) {
;     LAS unsigned char* Kr = lds; LAS unsigned char* Vt = lds + 128 * 528; LAS float* red = (LAS float*)(lds + 128 * 528 + 256 * 264);
;     const int lane = tid & 63, wid = tid >> 6, r = lane & 31, hh = lane >> 5;
;     const bf16_t* zc = Z + (size_t)(n * 128) * INW;
; #pragma unroll
;     for (int k = 0; k < 8; ++k) { const int it = k * 512 + tid, row = it >> 5, c = it & 31;
;         *(LAS u32x4*)(Kr + row * 528 + c * 16) = *(const u32x4*)(zc + (size_t)row * INW + C_RK + h * 256 + c * 8); }
;     stage_T128x256(Vt, zc + C_RV + h * 256, tid);
;     const int it_ = wid >> 1, dh = wid & 1;
;     bf16x8 qf[16];
;     { const bf16_t* qp = zc + (size_t)(32 * it_ + r) * INW + C_RQ + h * 256 + 8 * hh;
; #pragma unroll
;       for (int s = 0; s < 16; ++s) qf[s] = *(const bf16x8*)(qp + 16 * s); }
;     f32x16 acc[4];
; #pragma unroll
;     for (int i = 0; i < 4; ++i) acc[i] = zero16();
;     const float gm = gamma_of(h);
;     __syncthreads();
; __global__ void __launch_bounds__(512, 2) fwd_kernel(Args a) {
;     ...
;     if (IN(4)) for (int rep_ = 0; rep_ < 1 + ((DUPMASK >> 4) & 1); ++rep_) { if (rep_) xcd_barrier(bar);
;         for (int u = bx; u < 256; u += G) ret_step2(lds, Z, SP, MIX, rng, u >> 2, u & 3, tid);
;         for (int u = bx; u < 256; u += G) attn_prompt_unit(lds, Z, MIX, gq, gk, sinks, out + O_KP, out + O_VP, u >> 2, (u >> 1) & 1, u & 1, tid);
;         {
;             LAS float* scr = (LAS float*)(lds + wid * 17408);
;             p0_convert(ResRest{w_out, w_up, w_dn, WOUT, WUP, WDN, ln2_g}, bx * 8 + wid, G * 8, NP0_REST, scr, lane);
;         }
.LBB0_403:
	s_mov_b32 s99, 0
	s_cmp_lt_i32 s62, 5
	s_cselect_b64 s[2:3], -1, 0
	s_and_b64 s[30:31], s[2:3], s[0:1]
	s_andn2_b64 vcc, exec, s[30:31]
	s_cbranch_vccnz .LBB0_457
	v_writelane_b32 v254, s30, 41
	s_cmpk_gt_i32 s92, 0xff
	s_nop 0
	v_writelane_b32 v254, s31, 42
	s_cbranch_scc1 .LBB0_437
	s_bfe_u32 s98, s92, 0x10002
	s_cbranch_scc0 .Lp4_r12
	s_mov_b32 s99, 1
	s_branch .LBB0_437
.Lp4_r12:
	v_add_u32_e32 v200, 0x200, v253
	v_lshrrev_b32_e32 v6, 5, v200
	v_mul_u32_u24_e32 v4, 0x1500, v6
	v_mul_u32_u24_e32 v7, 0x210, v6
	v_add_u32_e32 v6, 0x600, v253
	v_lshrrev_b32_e32 v8, 5, v6
	v_and_b32_e32 v154, 31, v253
	v_mul_u32_u24_e32 v6, 0x1500, v8
	v_mul_u32_u24_e32 v9, 0x210, v8
	v_add_u32_e32 v8, 0xa00, v253
	v_bfe_u32 v25, v253, 6, 1
	v_lshrrev_b32_e32 v10, 5, v8
	v_bfe_u32 v15, v253, 5, 1
	v_lshlrev_b32_e32 v33, 16, v25
	v_lshlrev_b32_e32 v34, 9, v154
	v_mul_u32_u24_e32 v8, 0x1500, v10
	v_mul_u32_u24_e32 v11, 0x210, v10
	v_add_u32_e32 v10, 0xe00, v253
	v_lshlrev_b32_e32 v156, 3, v15
	v_lshlrev_b32_e32 v29, 4, v15
	v_lshlrev_b32_e32 v211, 2, v15
	v_add3_u32 v33, 0, v33, v34
	v_bitop3_b32 v34, v15, v154, 2 bitop3:0x36
	v_bitop3_b32 v35, v15, v154, 4 bitop3:0x36
	v_bitop3_b32 v36, v15, v154, 6 bitop3:0x36
	v_bitop3_b32 v37, v15, v154, 8 bitop3:0x36
	v_bitop3_b32 v38, v15, v154, 10 bitop3:0x36
	v_bitop3_b32 v39, v15, v154, 12 bitop3:0x36
	v_bitop3_b32 v40, v15, v154, 14 bitop3:0x36
	v_bitop3_b32 v41, v15, v154, 16 bitop3:0x36
	v_bitop3_b32 v42, v15, v154, 18 bitop3:0x36
	v_bitop3_b32 v43, v15, v154, 20 bitop3:0x36
	v_bitop3_b32 v44, v15, v154, 22 bitop3:0x36
	v_bitop3_b32 v45, v15, v154, 24 bitop3:0x36
	v_bitop3_b32 v46, v15, v154, 26 bitop3:0x36
	v_bitop3_b32 v47, v15, v154, 28 bitop3:0x36
	v_cmp_eq_u32_e64 s[38:39], 0, v15
	v_lshlrev_b32_e32 v15, 7, v252
	s_add_i32 s40, 0, 0x21000
	v_lshlrev_b32_e32 v49, 2, v154
	v_lshrrev_b32_e32 v199, 5, v253
	v_lshrrev_b32_e32 v12, 5, v10
	v_bfe_u32 v14, v253, 2, 4
	v_lshrrev_b32_e32 v153, 7, v253
	v_add3_u32 v218, s40, v15, v49
	v_lshlrev_b32_e32 v15, 5, v252
	v_mul_u32_u24_e32 v10, 0x1500, v12
	v_mul_u32_u24_e32 v13, 0x210, v12
	v_and_b32_e32 v12, 3, v253
	v_lshrrev_b32_e32 v16, 4, v253
	v_and_or_b32 v17, v199, 16, v14
	s_add_i32 s2, 0, 0x10800
	v_lshl_or_b32 v24, v153, 5, v154
	v_lshl_or_b32 v26, v25, 7, v154
	v_bitop3_b32 v15, v15, 32, v154 bitop3:0x36
	v_and_or_b32 v16, v16, 28, v12
	v_mul_u32_u24_e32 v14, 0x2a00, v17
	v_lshl_add_u32 v19, v17, 2, s2
	v_add_u32_e32 v18, 16, v17
	v_or_b32_e32 v20, 32, v17
	v_add_u32_e32 v17, 48, v17
	v_mul_u32_u24_e32 v22, 0x1500, v24
	s_movk_i32 s3, 0x108
	v_mul_u32_u24_e32 v27, 0x108, v26
	v_add_u32_e32 v31, 16, v199
	v_lshl_add_u32 v219, v15, 2, s40
	v_lshlrev_b32_e32 v15, 9, v25
	v_mul_u32_u24_e32 v24, 0x410, v24
	s_ashr_i32 s93, s92, 31
	v_mov_b32_e32 v159, 0
	v_lshlrev_b32_e32 v12, 3, v16
	v_mul_u32_u24_e32 v21, 0x840, v16
	v_mul_u32_u24_e32 v16, 0x2a00, v18
	v_lshl_add_u32 v23, v18, 2, s2
	v_mul_u32_u24_e32 v18, 0x2a00, v20
	v_lshl_add_u32 v28, v20, 2, s2
	v_mul_u32_u24_e32 v20, 0x2a00, v17
	v_lshl_add_u32 v17, v17, 2, s2
	v_bitop3_b32 v31, v31, v253, 31 bitop3:0x78
	v_add3_u32 v15, 0, v24, v15
	v_lshlrev_b32_e32 v24, 5, v253
	v_add3_u32 v220, s2, v156, v27
	v_mad_u32_u24 v221, v26, s3, v156
	s_lshl_b64 s[2:3], s[92:93], 17
	v_and_b32_e32 v158, 0x3e0, v24
	v_lshl_or_b32 v24, v199, 9, s2
	v_mov_b32_e32 v25, s3
	v_lshlrev_b32_e32 v26, 4, v31
	v_mov_b32_e32 v27, v159
	v_lshl_add_u64 v[26:27], v[24:25], 0, v[26:27]
	v_bitop3_b32 v30, v253, v199, 31 bitop3:0x6c
	v_lshl_add_u64 v[26:27], s[60:61], 0, v[26:27]
	s_mov_b64 s[2:3], 0x13c02000
	v_lshl_add_u64 v[164:165], v[26:27], 0, s[2:3]
	s_ashr_i32 s3, s64, 31
	s_mov_b32 s2, s64
	v_lshl_or_b32 v24, v30, 4, v24
	v_readlane_b32 s68, v254, 7
	s_lshl_b64 s[48:49], s[2:3], 17
	v_lshl_add_u64 v[24:25], s[60:61], 0, v[24:25]
	s_mov_b64 s[2:3], 0x13c00000
	v_lshlrev_b32_e32 v1, 4, v154
	v_readlane_b32 s72, v254, 11
	v_readlane_b32 s73, v254, 12
	v_lshl_add_u64 v[166:167], v[24:25], 0, s[2:3]
	v_mul_u32_u24_e32 v24, 0x410, v199
	v_lshl_add_u64 v[160:161], s[72:73], 0, v[158:159]
	v_add3_u32 v223, v24, v158, 0
	v_lshl_or_b32 v158, v199, 12, v1
; #define LAS __attribute__((address_space(3)))
; #define MFMA32(a, b, c) __builtin_amdgcn_mfma_f32_32x32x16_bf16((a), (b), (c), 0, 0, 0)
; DI int crow(int reg, int h) { return (reg & 3) + 8 * (reg >> 2) + 4 * h; }
; DI void ret_step2(LAS unsigned char* lds, const bf16_t* Z, const bf16_t* SP, bf16_t* MIX, const float* rng, int n, int h, int tid) {
;     ...
;     for (int jt = 0; jt <= it_; ++jt) {
;         f32x16 X = zero16();
; #pragma unroll
;         for (int s = 0; s < 16; ++s) { const bf16x8 A = *(const LAS bf16x8*)(Kr + (32 * jt + r) * 528 + (16 * s + 8 * hh) * 2); X = MFMA32(A, qf[s], X); }
;         if (jt == it_) {
; #pragma unroll
;             for (int i = 0; i < 16; ++i) X[i] = (crow(i, hh) > r) ? 0.f : X[i];
;         }
; #pragma unroll
;         for (int s2 = 0; s2 < 2; ++s2) { const bf16x8 xs = pack8(X, s2);
; #pragma unroll
;             for (int dt = 0; dt < 4; ++dt) { const LAS unsigned char* pa = Vt + (128 * dh + 32 * dt + r) * 264 + (32 * jt + 16 * s2 + 4 * hh) * 2;
;                 const bf16x8 A = cat4(*(const LAS s16x4*)pa, *(const LAS s16x4*)(pa + 16)); acc[dt] = MFMA32(A, xs, acc[dt]); } }
;     }
;     { const float ig = 1.0f / gm;
; #pragma unroll
;       for (int dt = 0; dt < 4; ++dt) acc[dt] = acc[dt] * ig; }
;     __syncthreads();
;     {
;         const bf16_t* spg = SP + (size_t)(n * 4 + h) * 65536;
;         const bf16_t* ge = spg + (size_t)(tid >> 5) * 256 + ((tid & 31) ^ (tid >> 5)) * 8;
;         const bf16_t* go = spg + (size_t)(tid >> 5) * 256 + ((tid & 31) ^ (16 + (tid >> 5))) * 8;
;         LAS unsigned char* ld = lds + wid * 1024;
; #pragma unroll 1
;         for (int k = 0; k < 16; k += 2) {
;             __builtin_amdgcn_global_load_lds((const unsigned*)(ge + (size_t)k * 4096), (LAS unsigned*)(ld + k * 8192), 16, 0, 0);
;             __builtin_amdgcn_global_load_lds((const unsigned*)(go + (size_t)(k + 1) * 4096), (LAS unsigned*)(ld + (k + 1) * 8192), 16, 0, 0);
;         }
;         asm volatile("s_waitcnt vmcnt(0)" ::: "memory");
;     }
;     __syncthreads();
; #pragma unroll
;     for (int dt = 0; dt < 4; ++dt)
; #pragma unroll
;         for (int s = 0; s < 16; ++s) { const int rw = 128 * dh + 32 * dt + r; const bf16x8 A = *(const LAS bf16x8*)(lds + rw * 512 + (((2 * s + hh) ^ (rw & 31)) * 16)); acc[dt] = MFMA32(A, qf[s], acc[dt]); }
	v_lshl_add_u64 v[24:25], s[60:61], 0, v[158:159]
	s_mov_b64 s[2:3], 0x8000800
	v_lshl_add_u64 v[168:169], v[24:25], 0, s[2:3]
	v_mul_u32_u24_e32 v24, 0x2a00, v199
	v_lshlrev_b32_e32 v0, 3, v154
	v_bitop3_b32 v32, v199, v154, 1 bitop3:0x6c
	v_bitop3_b32 v48, v199, v154, 30 bitop3:0x36
	v_mul_hi_u32_u24_e32 v25, 0x2a00, v199
	v_or_b32_e32 v24, v24, v1
	v_add_u32_e32 v3, 0, v1
	v_mul_u32_u24_e32 v2, 0x1500, v199
	s_movk_i32 s33, 0x210
	v_mul_u32_u24_e32 v5, 0x210, v199
	s_movk_i32 s0, 0x7f
	v_or_b32_e32 v215, 2, v211
	v_or_b32_e32 v214, 3, v211
	v_or_b32_e32 v213, 8, v211
	v_or_b32_e32 v212, 9, v211
	v_or_b32_e32 v210, 10, v211
	v_or_b32_e32 v209, 11, v211
	v_or_b32_e32 v208, 16, v211
	v_or_b32_e32 v207, 17, v211
	v_or_b32_e32 v206, 18, v211
	v_or_b32_e32 v205, 19, v211
	v_or_b32_e32 v204, 24, v211
	v_or_b32_e32 v203, 25, v211
	v_or_b32_e32 v202, 26, v211
	v_or_b32_e32 v201, 27, v211
	v_lshlrev_b32_e32 v32, 4, v32
	v_lshlrev_b32_e32 v34, 4, v34
	v_lshlrev_b32_e32 v35, 4, v35
	v_lshlrev_b32_e32 v36, 4, v36
	v_lshlrev_b32_e32 v37, 4, v37
	v_lshlrev_b32_e32 v38, 4, v38
	v_lshlrev_b32_e32 v39, 4, v39
	v_lshlrev_b32_e32 v40, 4, v40
	v_lshlrev_b32_e32 v41, 4, v41
	v_lshlrev_b32_e32 v42, 4, v42
	v_lshlrev_b32_e32 v43, 4, v43
	v_lshlrev_b32_e32 v44, 4, v44
	v_lshlrev_b32_e32 v45, 4, v45
	v_lshlrev_b32_e32 v46, 4, v46
	v_lshlrev_b32_e32 v47, 4, v47
	v_lshlrev_b32_e32 v48, 4, v48
	v_readlane_b32 s74, v254, 13
	v_readlane_b32 s75, v254, 14
	v_readlane_b32 s76, v254, 15
	v_lshl_add_u64 v[24:25], s[60:61], 0, v[24:25]
	s_mov_b64 s[2:3], 0xa402200
	v_lshlrev_b32_e32 v172, 1, v0
	v_mbcnt_lo_u32_b32 v0, -1, 0
	s_mov_b32 s43, 0
	v_add_u32_e32 v157, 0, v29
	v_cmp_lt_u32_e64 s[0:1], s0, v253
	v_cmp_gt_u32_e64 s[4:5], v211, v154
	v_cmp_lt_u32_e64 s[6:7], v211, v154
	v_cmp_gt_u32_e64 s[8:9], v215, v154
	v_cmp_gt_u32_e64 s[10:11], v214, v154
	v_cmp_gt_u32_e64 s[12:13], v213, v154
	v_cmp_gt_u32_e64 s[14:15], v212, v154
	v_cmp_gt_u32_e64 s[16:17], v210, v154
	v_cmp_gt_u32_e64 s[18:19], v209, v154
	v_cmp_gt_u32_e64 s[20:21], v208, v154
	v_cmp_gt_u32_e64 s[22:23], v207, v154
	v_cmp_gt_u32_e64 s[24:25], v206, v154
	v_cmp_gt_u32_e64 s[26:27], v205, v154
	v_cmp_gt_u32_e64 s[28:29], v204, v154
	v_cmp_gt_u32_e64 s[30:31], v203, v154
	v_cmp_gt_u32_e64 s[34:35], v202, v154
	v_cmp_gt_u32_e64 s[36:37], v201, v154
	v_lshl_add_u32 v216, v252, 10, 0
	v_mad_u32_u24 v222, v154, s33, v29
	v_lshl_add_u64 v[170:171], v[24:25], 0, s[2:3]
	v_lshlrev_b32_e32 v158, 1, v2
	s_movk_i32 s72, 0x1000
	v_add_u32_e32 v224, v3, v5
	v_lshlrev_b32_e32 v174, 1, v4
	v_add_u32_e32 v225, v3, v7
	v_lshlrev_b32_e32 v176, 1, v6
	v_add_u32_e32 v226, v3, v9
	v_lshlrev_b32_e32 v178, 1, v8
	v_add_u32_e32 v227, v3, v11
	v_lshlrev_b32_e32 v180, 1, v10
	v_add_u32_e32 v228, v3, v13
	v_lshlrev_b32_e32 v182, 1, v12
	v_lshlrev_b32_e32 v184, 1, v14
	s_movk_i32 s73, 0x2000
	v_add_u32_e32 v229, v19, v21
	s_mov_b32 s74, 0xffff0000
	v_lshlrev_b32_e32 v186, 1, v16
	v_add_u32_e32 v230, v23, v21
	v_lshlrev_b32_e32 v188, 1, v18
	v_add_u32_e32 v231, v28, v21
	v_lshlrev_b32_e32 v190, 1, v20
	v_add_u32_e32 v232, v17, v21
	v_lshlrev_b32_e32 v192, 1, v22
	v_lshlrev_b32_e32 v162, 1, v156
	s_mov_b64 s[50:51], 0x4000
	v_add_u32_e32 v233, v33, v32
	v_add_u32_e32 v234, v33, v34
	v_add_u32_e32 v235, v33, v35
	v_add_u32_e32 v236, v33, v36
	v_add_u32_e32 v237, v33, v37
	v_add_u32_e32 v238, v33, v38
	v_add_u32_e32 v239, v33, v39
	v_add_u32_e32 v240, v33, v40
	v_add_u32_e32 v241, v33, v41
	v_add_u32_e32 v242, v33, v42
	v_add_u32_e32 v243, v33, v43
	v_add_u32_e32 v244, v33, v44
	v_add_u32_e32 v245, v33, v45
	v_add_u32_e32 v246, v33, v46
	v_add_u32_e32 v247, v33, v47
	v_add_u32_e32 v248, v33, v48
	v_mov_b32_e32 v249, 0x358637bd
	v_add_u32_e32 v250, v15, v29
	v_mov_b32_e32 v251, 0x42800000
	v_mbcnt_hi_u32_b32 v217, -1, v0
	s_mov_b32 s75, s92
	s_mov_b32 s76, s92
	v_readlane_b32 s69, v254, 8
	v_readlane_b32 s70, v254, 9
	v_readlane_b32 s71, v254, 10
	v_readlane_b32 s77, v254, 16
	v_readlane_b32 s78, v254, 17
	v_readlane_b32 s79, v254, 18
	v_readlane_b32 s80, v254, 19
	v_readlane_b32 s81, v254, 20
	v_readlane_b32 s82, v254, 21
	v_readlane_b32 s83, v254, 22

; #define LAS __attribute__((address_space(3)))
; template <class Resolve>
; DI void p0_convert(const Resolve R, int first, int stride, int total, LAS float* scr, int lane) {
;     for (int it = first; it < total; it += 2 * stride) {
;         const bool two = it + stride < total;
; __global__ void __launch_bounds__(512, 2) fwd_kernel(Args a) {
;     ...
;         {
;             LAS float* scr = (LAS float*)(lds + wid * 17408);
;             p0_convert(ResRest{w_out, w_up, w_dn, WOUT, WUP, WDN, ln2_g}, bx * 8 + wid, G * 8, NP0_REST, scr, lane);
;         }
.LBB0_437:
	s_lshl_b32 s0, s92, 3
	v_readlane_b32 s1, v254, 6
	s_add_i32 s20, s1, s0
	v_readlane_b32 s30, v254, 41
	s_cmpk_gt_i32 s20, 0x23ff
	v_readlane_b32 s31, v254, 42
	s_cbranch_scc1 .LBB0_457
	s_cmp_eq_u32 s99, 2
	s_cbranch_scc1 .LBB0_457
	v_readlane_b32 s0, v254, 6
	s_mulk_i32 s0, 0x4400
	v_lshlrev_b32_e32 v0, 2, v253
	s_add_i32 s0, s0, 0
	v_lshrrev_b32_e32 v72, 3, v152
	v_and_b32_e32 v0, 28, v0
	v_and_b32_e32 v1, 7, v253
	v_mov_b32_e32 v65, 0
	v_lshl_add_u32 v3, v1, 4, s0
	v_mul_u32_u24_e32 v4, 0x84, v72
	v_lshlrev_b32_e32 v2, 3, v1
	v_mul_u32_u24_e32 v1, 0x420, v1
	v_lshlrev_b32_e32 v5, 2, v72
	v_lshlrev_b32_e32 v66, 2, v0
	s_lshl_b32 s21, s64, 3
	v_or_b32_e32 v73, 8, v72
	v_or_b32_e32 v74, 16, v72
	v_or_b32_e32 v75, 24, v72
	v_add3_u32 v76, s0, v1, v5
	s_lshl_b32 s22, s64, 4
	v_mov_b32_e32 v68, v66
	v_mov_b32_e32 v69, v65
	v_lshlrev_b32_e32 v64, 1, v2
	v_add_u32_e32 v77, v3, v4
	s_branch .LBB0_440

; #define LAS __attribute__((address_space(3)))
; __global__ void __launch_bounds__(512, 2) fwd_kernel(Args a) {
;     ...
;     if (IN(4)) for (int rep_ = 0; rep_ < 1 + ((DUPMASK >> 4) & 1); ++rep_) { if (rep_) xcd_barrier(bar);
;         for (int u = bx; u < 256; u += G) ret_step2(lds, Z, SP, MIX, rng, u >> 2, u & 3, tid);
;         for (int u = bx; u < 256; u += G) attn_prompt_unit(lds, Z, MIX, gq, gk, sinks, out + O_KP, out + O_VP, u >> 2, (u >> 1) & 1, u & 1, tid);
;         {
;             LAS float* scr = (LAS float*)(lds + wid * 17408);
;             p0_convert(ResRest{w_out, w_up, w_dn, WOUT, WUP, WDN, ln2_g}, bx * 8 + wid, G * 8, NP0_REST, scr, lane);
;         }
;     }
.LBB0_457:
	s_cmp_eq_u32 s99, 1
	s_cbranch_scc0 .Lp4_done
	s_mov_b32 s99, 2
	s_mov_b64 exec, -1
	s_waitcnt lgkmcnt(0)
	s_barrier
	s_branch .Lp4_r12
